# v61 + grid barrier: last-arriving XCD leader bumps all per-XCD release words itself (no relay by the other leaders); waiters keep polling their own XCD word
# baseline (speedup 1.0000x reference)
; __device__ __forceinline__ unsigned xb_ld(unsigned* p)              { return __hip_atomic_load(p, __ATOMIC_RELAXED, __HIP_MEMORY_SCOPE_AGENT); }
; __device__ __forceinline__ unsigned xb_add(unsigned* p, unsigned v) { return __hip_atomic_fetch_add(p, v, __ATOMIC_RELAXED, __HIP_MEMORY_SCOPE_AGENT); }
; #define XB_SPIN(cond, bar) do { unsigned _sp = 0; while (cond) { __builtin_amdgcn_s_sleep(1); \
;     if ((++_sp & 255u) == 0u) { if (xb_ld(&(bar)[XB_TMO])) break; if (_sp > XB_SPIN_CAP) { atomicAdd(&(bar)[XB_TMO], 1u); break; } } } } while (0)
; __device__ __forceinline__ void xcd_barrier(const XcdBarrier& b) {
;     ...
;         if (old + 1u == (gen + 1u) * nloc) {
;             __builtin_amdgcn_fence(__ATOMIC_RELEASE, "agent");
;             asm volatile("s_waitcnt vmcnt(0)" ::: "memory");
;             const unsigned og = xb_add(&bar[XB_TOP], 1u);
;             const unsigned tg = og / nx;
;             if (og + 1u == (tg + 1u) * nx) xb_add(&bar[XB_TOPGEN], 1u);
;             else XB_SPIN(xb_ld(&bar[XB_TOPGEN]) == tg, bar);
;             __builtin_amdgcn_fence(__ATOMIC_ACQUIRE, "agent");
;             xb_add(&bar[XB_XGEN(b.x)], 1u);
.LBB0_229:
	s_andn2_saveexec_b64 s[4:5], s[10:11]
	s_cbranch_execz .LBB0_245
	buffer_wbl2 sc1
	s_waitcnt lgkmcnt(0)
	s_waitcnt vmcnt(0)
	v_mov_b32_e32 v1, 0x3000
	global_atomic_add v3, v1, v252, s[88:89] offset:1024 sc0
	v_cvt_f32_u32_e32 v1, v2
	v_sub_u32_e32 v4, 0, v2
	s_add_u32 s10, s88, 0x3500
	s_addc_u32 s11, s89, 0
	v_rcp_iflag_f32_e32 v1, v1
	s_mov_b64 s[14:15], -1
	v_mul_f32_e32 v1, 0x4f7ffffe, v1
	v_cvt_u32_f32_e32 v1, v1
	v_mul_lo_u32 v4, v4, v1
	v_mul_hi_u32 v4, v1, v4
	v_add_u32_e32 v1, v1, v4
	s_waitcnt vmcnt(0)
	v_mul_hi_u32 v1, v3, v1
	v_mul_lo_u32 v4, v1, v2
	v_sub_u32_e32 v4, v3, v4
	v_cmp_ge_u32_e32 vcc, v4, v2
	v_add_u32_e32 v5, 1, v1
	v_add_u32_e32 v3, 1, v3
	v_cndmask_b32_e32 v1, v1, v5, vcc
	v_sub_u32_e32 v5, v4, v2
	v_cndmask_b32_e32 v4, v4, v5, vcc
	v_cmp_ge_u32_e32 vcc, v4, v2
	v_add_u32_e32 v4, 1, v1
	s_nop 0
	v_cndmask_b32_e32 v1, v1, v4, vcc
	v_mul_lo_u32 v4, v2, v1
	v_add_u32_e32 v2, v4, v2
	v_cmp_ne_u32_e32 vcc, v3, v2
	v_mov_b64_e32 v[2:3], s[10:11]
	s_cbranch_vccnz .Lxb_notlast_0
	global_atomic_add v253, v252, s[88:89] offset:1024
	global_atomic_add v253, v252, s[88:89] offset:1280
	global_atomic_add v253, v252, s[88:89] offset:1536
	global_atomic_add v253, v252, s[88:89] offset:1792
	global_atomic_add v253, v252, s[88:89] offset:2048
	global_atomic_add v253, v252, s[88:89] offset:2304
	global_atomic_add v253, v252, s[88:89] offset:2560
	global_atomic_add v253, v252, s[88:89] offset:2816
	global_atomic_add v253, v252, s[88:89] offset:3072
	global_atomic_add v253, v252, s[88:89] offset:3328
	global_atomic_add v253, v252, s[88:89] offset:3584
	global_atomic_add v253, v252, s[88:89] offset:3840
.Lxb_notlast_0:
	s_and_saveexec_b64 s[12:13], vcc
	s_cbranch_execz .LBB0_242
	global_load_dword v2, v0, s[10:11] sc1
	s_mov_b64 s[18:19], 0
	s_waitcnt vmcnt(0)
	v_cmp_eq_u32_e32 vcc, v2, v1
	s_and_saveexec_b64 s[16:17], vcc
	s_cbranch_execz .LBB0_241
	s_add_u32 s14, s88, 0x200
	s_addc_u32 s15, s89, 0
	s_mov_b32 s4, 1
	s_branch .LBB0_234

; __device__ __forceinline__ unsigned xb_ld(unsigned* p)              { return __hip_atomic_load(p, __ATOMIC_RELAXED, __HIP_MEMORY_SCOPE_AGENT); }
; __device__ __forceinline__ unsigned xb_add(unsigned* p, unsigned v) { return __hip_atomic_fetch_add(p, v, __ATOMIC_RELAXED, __HIP_MEMORY_SCOPE_AGENT); }
; #define XB_SPIN(cond, bar) do { unsigned _sp = 0; while (cond) { __builtin_amdgcn_s_sleep(1); \
;     if ((++_sp & 255u) == 0u) { if (xb_ld(&(bar)[XB_TMO])) break; if (_sp > XB_SPIN_CAP) { atomicAdd(&(bar)[XB_TMO], 1u); break; } } } } while (0)
; __device__ __forceinline__ void xcd_barrier(const XcdBarrier& b) {
;     ...
;             if (og + 1u == (tg + 1u) * nx) xb_add(&bar[XB_TOPGEN], 1u);
;             else XB_SPIN(xb_ld(&bar[XB_TOPGEN]) == tg, bar);
.Lxb_notlast_1:
	s_and_saveexec_b64 s[12:13], vcc
	s_cbranch_execz .LBB0_336
	global_load_dword v2, v0, s[10:11] sc1
	s_mov_b64 s[18:19], 0
	s_waitcnt vmcnt(0)
	v_cmp_eq_u32_e32 vcc, v2, v1
	s_and_saveexec_b64 s[16:17], vcc
	s_cbranch_execz .LBB0_335
	s_add_u32 s14, s88, 0x200
	s_addc_u32 s15, s89, 0
	s_mov_b32 s2, 1
	s_branch .LBB0_328

; __device__ __forceinline__ unsigned xb_ld(unsigned* p)              { return __hip_atomic_load(p, __ATOMIC_RELAXED, __HIP_MEMORY_SCOPE_AGENT); }
; __device__ __forceinline__ unsigned xb_add(unsigned* p, unsigned v) { return __hip_atomic_fetch_add(p, v, __ATOMIC_RELAXED, __HIP_MEMORY_SCOPE_AGENT); }
; #define XB_SPIN(cond, bar) do { unsigned _sp = 0; while (cond) { __builtin_amdgcn_s_sleep(1); \
;     if ((++_sp & 255u) == 0u) { if (xb_ld(&(bar)[XB_TMO])) break; if (_sp > XB_SPIN_CAP) { atomicAdd(&(bar)[XB_TMO], 1u); break; } } } } while (0)
; __device__ __forceinline__ void xcd_barrier(const XcdBarrier& b) {
;     ...
;         if (old + 1u == (gen + 1u) * nloc) {
;             __builtin_amdgcn_fence(__ATOMIC_RELEASE, "agent");
;             asm volatile("s_waitcnt vmcnt(0)" ::: "memory");
;             const unsigned og = xb_add(&bar[XB_TOP], 1u);
;             const unsigned tg = og / nx;
;             if (og + 1u == (tg + 1u) * nx) xb_add(&bar[XB_TOPGEN], 1u);
;             else XB_SPIN(xb_ld(&bar[XB_TOPGEN]) == tg, bar);
;             __builtin_amdgcn_fence(__ATOMIC_ACQUIRE, "agent");
;             xb_add(&bar[XB_XGEN(b.x)], 1u);
.LBB0_586:
	s_andn2_saveexec_b64 s[4:5], s[8:9]
	s_cbranch_execz .LBB0_602
	buffer_wbl2 sc1
	s_waitcnt lgkmcnt(0)
	s_waitcnt vmcnt(0)
	v_mov_b32_e32 v1, 0x3000
	global_atomic_add v3, v1, v252, s[88:89] offset:1024 sc0
	v_cvt_f32_u32_e32 v1, v2
	v_sub_u32_e32 v4, 0, v2
	s_add_u32 s8, s88, 0x3500
	s_addc_u32 s9, s89, 0
	v_rcp_iflag_f32_e32 v1, v1
	s_mov_b64 s[12:13], -1
	v_mul_f32_e32 v1, 0x4f7ffffe, v1
	v_cvt_u32_f32_e32 v1, v1
	v_mul_lo_u32 v4, v4, v1
	v_mul_hi_u32 v4, v1, v4
	v_add_u32_e32 v1, v1, v4
	s_waitcnt vmcnt(0)
	v_mul_hi_u32 v1, v3, v1
	v_mul_lo_u32 v4, v1, v2
	v_sub_u32_e32 v4, v3, v4
	v_cmp_ge_u32_e32 vcc, v4, v2
	v_add_u32_e32 v5, 1, v1
	v_add_u32_e32 v3, 1, v3
	v_cndmask_b32_e32 v1, v1, v5, vcc
	v_sub_u32_e32 v5, v4, v2
	v_cndmask_b32_e32 v4, v4, v5, vcc
	v_cmp_ge_u32_e32 vcc, v4, v2
	v_add_u32_e32 v4, 1, v1
	s_nop 0
	v_cndmask_b32_e32 v1, v1, v4, vcc
	v_mul_lo_u32 v4, v2, v1
	v_add_u32_e32 v2, v4, v2
	v_cmp_ne_u32_e32 vcc, v3, v2
	v_mov_b64_e32 v[2:3], s[8:9]
	s_cbranch_vccnz .Lxb_notlast_2
	global_atomic_add v253, v252, s[88:89] offset:1024
	global_atomic_add v253, v252, s[88:89] offset:1280
	global_atomic_add v253, v252, s[88:89] offset:1536
	global_atomic_add v253, v252, s[88:89] offset:1792
	global_atomic_add v253, v252, s[88:89] offset:2048
	global_atomic_add v253, v252, s[88:89] offset:2304
	global_atomic_add v253, v252, s[88:89] offset:2560
	global_atomic_add v253, v252, s[88:89] offset:2816
	global_atomic_add v253, v252, s[88:89] offset:3072
	global_atomic_add v253, v252, s[88:89] offset:3328
	global_atomic_add v253, v252, s[88:89] offset:3584
	global_atomic_add v253, v252, s[88:89] offset:3840
.Lxb_notlast_2:
	s_and_saveexec_b64 s[10:11], vcc
	s_cbranch_execz .LBB0_599
	global_load_dword v2, v0, s[8:9] sc1
	s_mov_b64 s[16:17], 0
	s_waitcnt vmcnt(0)
	v_cmp_eq_u32_e32 vcc, v2, v1
	s_and_saveexec_b64 s[14:15], vcc
	s_cbranch_execz .LBB0_598
	s_add_u32 s12, s88, 0x200
	s_addc_u32 s13, s89, 0
	s_mov_b32 s4, 1
	s_branch .LBB0_591

; __device__ __forceinline__ unsigned xb_ld(unsigned* p)              { return __hip_atomic_load(p, __ATOMIC_RELAXED, __HIP_MEMORY_SCOPE_AGENT); }
; __device__ __forceinline__ unsigned xb_add(unsigned* p, unsigned v) { return __hip_atomic_fetch_add(p, v, __ATOMIC_RELAXED, __HIP_MEMORY_SCOPE_AGENT); }
; #define XB_SPIN(cond, bar) do { unsigned _sp = 0; while (cond) { __builtin_amdgcn_s_sleep(1); \
;     if ((++_sp & 255u) == 0u) { if (xb_ld(&(bar)[XB_TMO])) break; if (_sp > XB_SPIN_CAP) { atomicAdd(&(bar)[XB_TMO], 1u); break; } } } } while (0)
; __device__ __forceinline__ void xcd_barrier(const XcdBarrier& b) {
;     ...
;         if (old + 1u == (gen + 1u) * nloc) {
;             __builtin_amdgcn_fence(__ATOMIC_RELEASE, "agent");
;             asm volatile("s_waitcnt vmcnt(0)" ::: "memory");
;             const unsigned og = xb_add(&bar[XB_TOP], 1u);
;             const unsigned tg = og / nx;
;             if (og + 1u == (tg + 1u) * nx) xb_add(&bar[XB_TOPGEN], 1u);
;             else XB_SPIN(xb_ld(&bar[XB_TOPGEN]) == tg, bar);
;             __builtin_amdgcn_fence(__ATOMIC_ACQUIRE, "agent");
;             xb_add(&bar[XB_XGEN(b.x)], 1u);
.LBB0_1291:
	s_andn2_saveexec_b64 s[8:9], s[8:9]
	s_cbranch_execz .LBB0_1307
	buffer_wbl2 sc1
	s_waitcnt lgkmcnt(0)
	s_waitcnt vmcnt(0)
	v_mov_b32_e32 v1, 0x3000
	global_atomic_add v3, v1, v252, s[88:89] offset:1024 sc0
	v_cvt_f32_u32_e32 v1, v2
	v_sub_u32_e32 v4, 0, v2
	s_add_u32 s8, s88, 0x3500
	s_addc_u32 s9, s89, 0
	v_rcp_iflag_f32_e32 v1, v1
	s_mov_b64 s[12:13], -1
	v_mul_f32_e32 v1, 0x4f7ffffe, v1
	v_cvt_u32_f32_e32 v1, v1
	v_mul_lo_u32 v4, v4, v1
	v_mul_hi_u32 v4, v1, v4
	v_add_u32_e32 v1, v1, v4
	s_waitcnt vmcnt(0)
	v_mul_hi_u32 v1, v3, v1
	v_mul_lo_u32 v4, v1, v2
	v_sub_u32_e32 v4, v3, v4
	v_cmp_ge_u32_e32 vcc, v4, v2
	v_add_u32_e32 v5, 1, v1
	v_add_u32_e32 v3, 1, v3
	v_cndmask_b32_e32 v1, v1, v5, vcc
	v_sub_u32_e32 v5, v4, v2
	v_cndmask_b32_e32 v4, v4, v5, vcc
	v_cmp_ge_u32_e32 vcc, v4, v2
	v_add_u32_e32 v4, 1, v1
	s_nop 0
	v_cndmask_b32_e32 v1, v1, v4, vcc
	v_mul_lo_u32 v4, v2, v1
	v_add_u32_e32 v2, v4, v2
	v_cmp_ne_u32_e32 vcc, v3, v2
	v_mov_b64_e32 v[2:3], s[8:9]
	s_cbranch_vccnz .Lxb_notlast_7
	global_atomic_add v253, v252, s[88:89] offset:1024
	global_atomic_add v253, v252, s[88:89] offset:1280
	global_atomic_add v253, v252, s[88:89] offset:1536
	global_atomic_add v253, v252, s[88:89] offset:1792
	global_atomic_add v253, v252, s[88:89] offset:2048
	global_atomic_add v253, v252, s[88:89] offset:2304
	global_atomic_add v253, v252, s[88:89] offset:2560
	global_atomic_add v253, v252, s[88:89] offset:2816
	global_atomic_add v253, v252, s[88:89] offset:3072
	global_atomic_add v253, v252, s[88:89] offset:3328
	global_atomic_add v253, v252, s[88:89] offset:3584
	global_atomic_add v253, v252, s[88:89] offset:3840
.Lxb_notlast_7:
	s_and_saveexec_b64 s[10:11], vcc
	s_cbranch_execz .LBB0_1304
	global_load_dword v2, v0, s[8:9] sc1
	s_mov_b64 s[16:17], 0
	s_waitcnt vmcnt(0)
	v_cmp_eq_u32_e32 vcc, v2, v1
	s_and_saveexec_b64 s[14:15], vcc
	s_cbranch_execz .LBB0_1303
	s_add_u32 s12, s88, 0x200
	s_addc_u32 s13, s89, 0
	s_mov_b32 s26, 1
	s_branch .LBB0_1296

; __device__ __forceinline__ unsigned xb_ld(unsigned* p)              { return __hip_atomic_load(p, __ATOMIC_RELAXED, __HIP_MEMORY_SCOPE_AGENT); }
; __device__ __forceinline__ unsigned xb_add(unsigned* p, unsigned v) { return __hip_atomic_fetch_add(p, v, __ATOMIC_RELAXED, __HIP_MEMORY_SCOPE_AGENT); }
; #define XB_SPIN(cond, bar) do { unsigned _sp = 0; while (cond) { __builtin_amdgcn_s_sleep(1); \
;     if ((++_sp & 255u) == 0u) { if (xb_ld(&(bar)[XB_TMO])) break; if (_sp > XB_SPIN_CAP) { atomicAdd(&(bar)[XB_TMO], 1u); break; } } } } while (0)
; __device__ __forceinline__ void xcd_barrier(const XcdBarrier& b) {
;     ...
;             if (og + 1u == (tg + 1u) * nx) xb_add(&bar[XB_TOPGEN], 1u);
;             else XB_SPIN(xb_ld(&bar[XB_TOPGEN]) == tg, bar);
.Lxb_notlast_8:
	s_and_saveexec_b64 s[10:11], vcc
	s_cbranch_execz .LBB0_1428
	global_load_dword v2, v0, s[8:9] sc1
	s_mov_b64 s[16:17], 0
	s_waitcnt vmcnt(0)
	v_cmp_eq_u32_e32 vcc, v2, v1
	s_and_saveexec_b64 s[14:15], vcc
	s_cbranch_execz .LBB0_1427
	s_add_u32 s12, s88, 0x200
	s_addc_u32 s13, s89, 0
	s_mov_b32 s2, 1
	s_branch .LBB0_1420

; __device__ __forceinline__ unsigned xb_ld(unsigned* p)              { return __hip_atomic_load(p, __ATOMIC_RELAXED, __HIP_MEMORY_SCOPE_AGENT); }
; __device__ __forceinline__ unsigned xb_add(unsigned* p, unsigned v) { return __hip_atomic_fetch_add(p, v, __ATOMIC_RELAXED, __HIP_MEMORY_SCOPE_AGENT); }
; #define XB_SPIN(cond, bar) do { unsigned _sp = 0; while (cond) { __builtin_amdgcn_s_sleep(1); \
;     if ((++_sp & 255u) == 0u) { if (xb_ld(&(bar)[XB_TMO])) break; if (_sp > XB_SPIN_CAP) { atomicAdd(&(bar)[XB_TMO], 1u); break; } } } } while (0)
; __device__ __forceinline__ void xcd_barrier(const XcdBarrier& b) {
;     ...
;         if (old + 1u == (gen + 1u) * nloc) {
;             __builtin_amdgcn_fence(__ATOMIC_RELEASE, "agent");
;             asm volatile("s_waitcnt vmcnt(0)" ::: "memory");
;             const unsigned og = xb_add(&bar[XB_TOP], 1u);
;             const unsigned tg = og / nx;
;             if (og + 1u == (tg + 1u) * nx) xb_add(&bar[XB_TOPGEN], 1u);
;             else XB_SPIN(xb_ld(&bar[XB_TOPGEN]) == tg, bar);
;             __builtin_amdgcn_fence(__ATOMIC_ACQUIRE, "agent");
;             xb_add(&bar[XB_XGEN(b.x)], 1u);
.LBB0_1485:
	s_andn2_saveexec_b64 s[4:5], s[6:7]
	s_cbranch_execz .LBB0_1501
	buffer_wbl2 sc1
	s_waitcnt lgkmcnt(0)
	s_waitcnt vmcnt(0)
	v_mov_b32_e32 v1, 0x3000
	v_mov_b32_e32 v2, 1
	global_atomic_add v1, v1, v2, s[88:89] offset:1024 sc0
	v_cvt_f32_u32_e32 v2, v0
	v_sub_u32_e32 v3, 0, v0
	s_add_u32 s6, s88, 0x3500
	s_addc_u32 s7, s89, 0
	v_rcp_iflag_f32_e32 v2, v2
	s_mov_b64 s[12:13], -1
	v_mul_f32_e32 v2, 0x4f7ffffe, v2
	v_cvt_u32_f32_e32 v2, v2
	v_mul_lo_u32 v3, v3, v2
	v_mul_hi_u32 v3, v2, v3
	v_add_u32_e32 v2, v2, v3
	s_waitcnt vmcnt(0)
	v_mul_hi_u32 v2, v1, v2
	v_mul_lo_u32 v4, v2, v0
	v_add_u32_e32 v3, 1, v1
	v_sub_u32_e32 v1, v1, v4
	v_add_u32_e32 v5, 1, v2
	v_cmp_ge_u32_e32 vcc, v1, v0
	v_sub_u32_e32 v4, v1, v0
	s_nop 0
	v_cndmask_b32_e32 v2, v2, v5, vcc
	v_cndmask_b32_e32 v1, v1, v4, vcc
	v_add_u32_e32 v4, 1, v2
	v_cmp_ge_u32_e32 vcc, v1, v0
	s_nop 1
	v_cndmask_b32_e32 v2, v2, v4, vcc
	v_mul_lo_u32 v1, v0, v2
	v_add_u32_e32 v0, v1, v0
	v_cmp_ne_u32_e32 vcc, v3, v0
	v_mov_b64_e32 v[0:1], s[6:7]
	s_cbranch_vccnz .Lxb_notlast_9
	v_mov_b32_e32 v4, 0x2000
	v_mov_b32_e32 v5, 1
	global_atomic_add v4, v5, s[88:89] offset:1024
	global_atomic_add v4, v5, s[88:89] offset:1280
	global_atomic_add v4, v5, s[88:89] offset:1536
	global_atomic_add v4, v5, s[88:89] offset:1792
	global_atomic_add v4, v5, s[88:89] offset:2048
	global_atomic_add v4, v5, s[88:89] offset:2304
	global_atomic_add v4, v5, s[88:89] offset:2560
	global_atomic_add v4, v5, s[88:89] offset:2816
	global_atomic_add v4, v5, s[88:89] offset:3072
	global_atomic_add v4, v5, s[88:89] offset:3328
	global_atomic_add v4, v5, s[88:89] offset:3584
	global_atomic_add v4, v5, s[88:89] offset:3840
.Lxb_notlast_9:
	s_and_saveexec_b64 s[8:9], vcc
	s_cbranch_execz .LBB0_1498
	v_mov_b32_e32 v0, 0
	global_load_dword v1, v0, s[6:7] sc1
	s_mov_b64 s[16:17], 0
	s_waitcnt vmcnt(0)
	v_cmp_eq_u32_e32 vcc, v1, v2
	s_and_saveexec_b64 s[14:15], vcc
	s_cbranch_execz .LBB0_1497
	s_add_u32 s12, s88, 0x200
	s_addc_u32 s13, s89, 0
	s_mov_b32 s24, 1
	s_mov_b64 s[4:5], 0
	s_branch .LBB0_1490
